# SSD-output units opened before the grid barrier at the end of the mixer phase (gated by a state-completion counter); P4 then only combines decode partials (measure 1)
# speedup vs baseline: 1.0087x; 1.0087x over previous
; #define PSTAMP(i) do { if (PROBE_SEG >= 20 && blockIdx.x == PROBE_BLK && threadIdx.x == 0) ((volatile LAS unsigned long long*)(ctlw + 32))[8 + (i)] = __builtin_amdgcn_s_memrealtime(); } while (0)
; #define QUEUE_LOOP(qi, total, ...) for (;;) { __syncthreads(); if (threadIdx.x == 0) ctlw[16] = __hip_atomic_fetch_add(qbase + 64 * (qi), 1u, __ATOMIC_RELAXED, __HIP_MEMORY_SCOPE_AGENT); \
;         __syncthreads(); const int u = (int)ctlw[16]; if (u >= (total)) break; __VA_ARGS__ }
; template <int MASK> __device__ __forceinline__ void phase3(const Params& p, LAS unsigned char* lds, volatile LAS unsigned* ctlw, int qset) {
;     ...
;     QUEUE_LOOP(0, U_SSDP, { ssd_state_unit<false>(p.ws, p.in[I_ALOG], p.in[I_SCONV], p.in[I_CONVW], p.in[I_CONVB], lds, u >> 5, (u >> 1) & 15, u & 1); })
;     QUEUE_LOOP(4, U_SSDSS, { ssd_state_unit<true>(p.ws, p.in[I_ALOG], p.in[I_SCONV], p.in[I_CONVW], p.in[I_CONVB], lds, u >> 1, 0, u & 1);
;         for (int hh = 0; hh < 4; ++hh)
;             ssd_out_unit<true>(p.ws, p.out, p.in[I_ALOG], p.in[I_DSKIP], p.in[I_SSDNW], p.in[I_SSM], p.in[I_SCONV], p.in[I_CONVW], p.in[I_CONVB], lds, u >> 1, 0, (u & 1) * 4 + hh); })
;     PSTAMP(5);
.LBB0_679:
	v_readlane_b32 s4, v254, 9
	s_sub_i32 s4, s4, 0x80
	s_min_u32 s99, s4, 16
	s_waitcnt vmcnt(0) lgkmcnt(0)
	s_barrier
	s_and_saveexec_b64 s[4:5], s[0:1]
	s_cbranch_execz .Lst_pub_done
	buffer_wbl2 sc1
	s_waitcnt vmcnt(0)
	v_mov_b32_e32 v2, 0xa00
	v_mov_b32_e32 v3, 1
	global_atomic_add v2, v3, s[90:91]
	s_waitcnt vmcnt(0)
.Lst_pub_done:
	s_or_b64 exec, exec, s[4:5]
	s_add_i32 s66, 0, 0x27e40
	v_bfrev_b32_e32 v2, 0.5
	s_mov_b32 s17, 0
	v_mov_b32_e32 v155, 0
	v_mov_b32_e32 v185, s66
	s_movk_i32 s67, 0x2000
	v_bfrev_b32_e32 v157, 1
	s_movk_i32 s74, 0x3600
	s_movk_i32 s75, 0x3000
	s_mov_b64 s[18:19], 0x1000
	s_mov_b64 s[20:21], 0x2000
	s_mov_b64 s[22:23], 0x2400
	s_movk_i32 s76, 0x110
	s_mov_b64 s[26:27], 0x3000
	s_add_i32 s77, 0, 0x1e000
	s_add_i32 s78, 0, 0x1e200
	s_add_i32 s79, 0, 0x1e1fc
	s_add_i32 s84, 0, 0x11000
	s_mov_b32 s85, 0xe000000
	v_lshl_or_b32 v186, v191, 2, v2
	v_mov_b32_e32 v187, 0x3000
	v_mov_b32_e32 v188, 0x8800
	v_mov_b32_e32 v189, 0x9900
	v_mov_b32_e32 v193, 0xaa00
	v_mov_b32_e32 v194, 0xbb00
	v_mov_b32_e32 v195, 0xcc00
	v_mov_b32_e32 v196, 0xdd00
	v_mov_b32_e32 v197, 0xee00
	v_mov_b32_e32 v198, 0xff00
	s_branch .LBB0_682

; #define PSTAMP(i) do { if (PROBE_SEG >= 20 && blockIdx.x == PROBE_BLK && threadIdx.x == 0) ((volatile LAS unsigned long long*)(ctlw + 32))[8 + (i)] = __builtin_amdgcn_s_memrealtime(); } while (0)
; #define STAMP() do { if (PROBE_SEG >= 0 && bx == 0 && tid == 0) { tst[nst] = __builtin_amdgcn_s_memrealtime(); } ++nst; } while (0)
; #define BOTH(k) (IN(k) && IN((k) + 1))
; template <int MASK> __device__ __forceinline__ void phase3(const Params& p, LAS unsigned char* lds, volatile LAS unsigned* ctlw, int qset) {
;     ...
;     __syncthreads();
;     PSTAMP(8);
; __global__ void __launch_bounds__(512, 2) hymba_fwd(Params p) {
;     ...
;     if (IN(3)) { phase3<31>(p, lds, ctlw, 0); if (BOTH(3)) GBAR(); STAMP(); }
;     if (IN(4)) { phase4(p, lds, ctlw, vcu, G, 0); if (BOTH(4)) GBAR(); STAMP(); }
.LBB0_1001:
	v_readlane_b32 s6, v254, 3
	v_readlane_b32 s7, v254, 4
	s_cmp_lt_i32 s7, 5
	s_waitcnt lgkmcnt(0)
	s_barrier
	s_cbranch_scc1 .LBB0_1051
	s_cmp_lg_u32 s98, 2
	s_cbranch_scc1 .Lp3_bar3
	s_mov_b32 s98, 3
	s_mov_b32 s5, 0x8000
	v_mov_b32_e32 v2, 0
.Lst_poll:
	global_load_dword v1, v2, s[90:91] offset:2560 sc1
	s_waitcnt vmcnt(0)
	v_readfirstlane_b32 s4, v1
	s_cmpk_gt_u32 s4, 0x93
	s_cbranch_scc1 .Lst_poll_done
	s_add_i32 s5, s5, -1
	s_cmp_eq_u32 s5, 0
	s_cbranch_scc1 .Lst_poll_done
	s_sleep 8
	s_branch .Lst_poll
.Lst_poll_done:
	buffer_inv sc1
	s_waitcnt vmcnt(0)
	s_branch .LBB0_1074
.Lp3_bar3:
	s_waitcnt vmcnt(0)
	s_barrier
	s_and_saveexec_b64 s[2:3], s[0:1]
	s_cbranch_execz .LBB0_1050
	v_readlane_b32 s0, v254, 8
	s_waitcnt vmcnt(0) expcnt(0) lgkmcnt(0)
	s_nop 0
	v_mov_b32_e32 v1, s0
	ds_read_b32 v3, v1
	ds_read_b32 v1, v1 offset:4
	s_waitcnt lgkmcnt(1)
	v_cmp_ne_u32_e32 vcc, 0, v3
	s_cbranch_vccnz .LBB0_1018
	v_readlane_b32 s0, v254, 0
	v_readlane_b32 s1, v254, 1
	s_load_dwordx2 s[6:7], s[0:1], 0x4
	s_add_u32 s0, s90, 0x4200
	s_addc_u32 s1, s91, 0
	s_add_u32 s4, s90, 0x4400
	s_addc_u32 s5, s91, 0
	v_readlane_b32 s8, v254, 2
	s_waitcnt lgkmcnt(0)
	s_mul_i32 s24, s6, s8
	s_add_u32 s6, s90, 0x4500
	s_mul_i32 s24, s24, s7
	s_addc_u32 s7, s91, 0
	s_add_u32 s8, s90, 0x4600
	s_addc_u32 s9, s91, 0
	s_add_u32 s10, s90, 0x4700
	s_addc_u32 s11, s91, 0
	s_add_u32 s12, s90, 0x4800
	s_addc_u32 s13, s91, 0
	s_add_u32 s14, s90, 0x4900
	s_addc_u32 s15, s91, 0
	s_add_u32 s16, s90, 0x4a00
	s_addc_u32 s17, s91, 0
	s_add_u32 s18, s90, 0x4b00
	s_addc_u32 s19, s91, 0
	s_add_u32 s20, s90, 0x4c00
	s_addc_u32 s21, s91, 0
	s_add_u32 s22, s90, 0x4d00
	s_addc_u32 s23, s91, 0
	s_add_u32 s26, s90, 0x4e00
	s_addc_u32 s27, s91, 0
	s_add_u32 s28, s90, 0x4f00
	s_addc_u32 s29, s91, 0
	s_add_u32 s30, s90, 0x5000
	s_addc_u32 s31, s91, 0
	s_add_u32 s34, s90, 0x5100
	s_addc_u32 s35, s91, 0
	s_add_u32 s40, s90, 0x5200
	s_addc_u32 s41, s91, 0
	s_add_u32 s42, s90, 0x5300
	s_addc_u32 s43, s91, 0
	s_mov_b32 s33, 1
	v_mov_b32_e32 v17, 0
	s_branch .LBB0_1006

; #define PSTAMP(i) do { if (PROBE_SEG >= 20 && blockIdx.x == PROBE_BLK && threadIdx.x == 0) ((volatile LAS unsigned long long*)(ctlw + 32))[8 + (i)] = __builtin_amdgcn_s_memrealtime(); } while (0)
; #define QUEUE_LOOP(qi, total, ...) for (;;) { __syncthreads(); if (threadIdx.x == 0) ctlw[16] = __hip_atomic_fetch_add(qbase + 64 * (qi), 1u, __ATOMIC_RELAXED, __HIP_MEMORY_SCOPE_AGENT); \
;         __syncthreads(); const int u = (int)ctlw[16]; if (u >= (total)) break; __VA_ARGS__ }
; #define STAMP() do { if (PROBE_SEG >= 0 && bx == 0 && tid == 0) { tst[nst] = __builtin_amdgcn_s_memrealtime(); } ++nst; } while (0)
; #define BOTH(k) (IN(k) && IN((k) + 1))
; __device__ __forceinline__ void phase4(const Params& p, LAS unsigned char* lds, volatile LAS unsigned* ctlw, int vcu, int G, int qset) {
;     ...
;     QUEUE_LOOP(5, NBATCH * 16 * 8, { const int v = NBATCH * 16 * 8 - 1 - u;
;         ssd_out_unit<false>(p.ws, p.out, p.in[I_ALOG], p.in[I_DSKIP], p.in[I_SSDNW], p.in[I_SSM], p.in[I_SCONV], p.in[I_CONVW], p.in[I_CONVB], lds, (v >> 3) & 3, v >> 5, v & 7); })
;     PSTAMP(1);
; __global__ void __launch_bounds__(512, 2) hymba_fwd(Params p) {
;     ...
;     if (IN(3)) { phase3<31>(p, lds, ctlw, 0); if (BOTH(3)) GBAR(); STAMP(); }
;     if (IN(4)) { phase4(p, lds, ctlw, vcu, G, 0); if (BOTH(4)) GBAR(); STAMP(); }
.LBB0_1134:
	s_cmp_eq_u32 s98, 3
	s_cbranch_scc0 .Lp4_after
	s_mov_b32 s98, 4
	s_waitcnt vmcnt(0) lgkmcnt(0)
	s_barrier
	v_readlane_b32 s6, v254, 3
	v_readlane_b32 s7, v254, 4
	s_branch .Lp3_bar3
